# v21: MoBA gating block (q.ksum scores + top-3) rewritten by hand: pipelined LDS reads, packed f32 FMA without shuffles, three exact arg-max passes; on top of v20
# speedup vs baseline: 1.0026x; 1.0026x over previous
; #define LAS __attribute__((address_space(3)))
;     ...
;     if (MOBA) {
;         if (j > 3) {
;             LAS float* KM = (LAS float*)(lds + ATT_KM);
;             for (int i = tid; i < j * 128; i += 512) KM[i] = kmean_bh[(size_t)(i >> 7) * D + (i & 127)];
;             __syncthreads();
;             float g[15];
; #pragma unroll
;             for (int kb = 0; kb < 15; ++kb) {
;                 float s = -INFINITY;
;                 if (kb < j) {
;                     s = 0.f;
; #pragma unroll
;                     for (int ks = 0; ks < 8; ++ks) {
;                         const f32x4 k0 = *(const LAS f32x4*)(KM + kb * 128 + 16 * ks + 8 * h2), k1 = *(const LAS f32x4*)(KM + kb * 128 + 16 * ks + 8 * h2 + 4);
;                         const u32x4 qq = __builtin_bit_cast(u32x4, qf[ks]);
;                         s += bflo(qq.x) * k0[0] + bfhi(qq.x) * k0[1] + bflo(qq.y) * k0[2] + bfhi(qq.y) * k0[3] + bflo(qq.z) * k1[0] + bfhi(qq.z) * k1[1] + bflo(qq.w) * k1[2] + bfhi(qq.w) * k1[3];
;                     }
;                     s += __shfl_xor(s, 32);
;                 }
;                 g[kb] = s;
.LBB0_379:
	s_or_b64 exec, exec, s[2:3]
	v_lshl_add_u32 v2, v155, 2, 0
	v_add_u32_e32 v157, 0x18000, v2
	s_waitcnt vmcnt(0) lgkmcnt(0)
	s_barrier
	ds_read_b128 v[4:7], v157
	ds_read_b128 v[8:11], v157 offset:16
	ds_read_b128 v[12:15], v157 offset:64
	ds_read_b128 v[16:19], v157 offset:80
	ds_read_b128 v[20:23], v157 offset:128
	ds_read_b128 v[24:27], v157 offset:144
	ds_read_b128 v[28:31], v157 offset:192
	ds_read_b128 v[32:35], v157 offset:208
	ds_read_b128 v[36:39], v157 offset:256
	ds_read_b128 v[40:43], v157 offset:272
	ds_read_b128 v[44:47], v157 offset:320
	ds_read_b128 v[48:51], v157 offset:336
	ds_read_b128 v[52:55], v157 offset:384
	ds_read_b128 v[56:59], v157 offset:400
	ds_read_b128 v[60:63], v157 offset:448
	ds_read_b128 v[64:67], v157 offset:464
	v_lshlrev_b32_e32 v162, 16, v114
	v_and_b32_e32 v163, 0xffff0000, v114
	v_lshlrev_b32_e32 v164, 16, v115
	v_and_b32_e32 v165, 0xffff0000, v115
	v_lshlrev_b32_e32 v166, 16, v116
	v_and_b32_e32 v167, 0xffff0000, v116
	v_lshlrev_b32_e32 v168, 16, v117
	v_and_b32_e32 v169, 0xffff0000, v117
	v_lshlrev_b32_e32 v170, 16, v118
	v_and_b32_e32 v171, 0xffff0000, v118
	v_lshlrev_b32_e32 v172, 16, v119
	v_and_b32_e32 v173, 0xffff0000, v119
	v_lshlrev_b32_e32 v174, 16, v120
	v_and_b32_e32 v175, 0xffff0000, v120
	v_lshlrev_b32_e32 v176, 16, v121
	v_and_b32_e32 v177, 0xffff0000, v121
	v_lshlrev_b32_e32 v178, 16, v122
	v_and_b32_e32 v179, 0xffff0000, v122
	v_lshlrev_b32_e32 v180, 16, v123
	v_and_b32_e32 v181, 0xffff0000, v123
	v_lshlrev_b32_e32 v182, 16, v124
	v_and_b32_e32 v183, 0xffff0000, v124
	v_lshlrev_b32_e32 v184, 16, v125
	v_and_b32_e32 v185, 0xffff0000, v125
	v_lshlrev_b32_e32 v186, 16, v126
	v_and_b32_e32 v187, 0xffff0000, v126
	v_lshlrev_b32_e32 v188, 16, v127
	v_and_b32_e32 v189, 0xffff0000, v127
	v_lshlrev_b32_e32 v190, 16, v128
	v_and_b32_e32 v191, 0xffff0000, v128
	v_lshlrev_b32_e32 v192, 16, v129
	v_and_b32_e32 v193, 0xffff0000, v129
	v_lshlrev_b32_e32 v194, 16, v130
	v_and_b32_e32 v195, 0xffff0000, v130
	v_lshlrev_b32_e32 v196, 16, v131
	v_and_b32_e32 v197, 0xffff0000, v131
	v_lshlrev_b32_e32 v198, 16, v132
	v_and_b32_e32 v199, 0xffff0000, v132
	v_lshlrev_b32_e32 v200, 16, v133
	v_and_b32_e32 v201, 0xffff0000, v133
	v_lshlrev_b32_e32 v202, 16, v134
	v_and_b32_e32 v203, 0xffff0000, v134
	v_lshlrev_b32_e32 v204, 16, v135
	v_and_b32_e32 v205, 0xffff0000, v135
	v_lshlrev_b32_e32 v206, 16, v136
	v_and_b32_e32 v207, 0xffff0000, v136
	v_lshlrev_b32_e32 v208, 16, v137
	v_and_b32_e32 v209, 0xffff0000, v137
	v_lshlrev_b32_e32 v210, 16, v138
	v_and_b32_e32 v211, 0xffff0000, v138
	v_lshlrev_b32_e32 v212, 16, v139
	v_and_b32_e32 v213, 0xffff0000, v139
	v_lshlrev_b32_e32 v214, 16, v140
	v_and_b32_e32 v215, 0xffff0000, v140
	v_lshlrev_b32_e32 v216, 16, v141
	v_and_b32_e32 v217, 0xffff0000, v141
	v_lshlrev_b32_e32 v218, 16, v142
	v_and_b32_e32 v219, 0xffff0000, v142
	v_lshlrev_b32_e32 v220, 16, v143
	v_and_b32_e32 v221, 0xffff0000, v143
	v_lshlrev_b32_e32 v222, 16, v144
	v_and_b32_e32 v223, 0xffff0000, v144
	v_lshlrev_b32_e32 v224, 16, v145
	v_and_b32_e32 v225, 0xffff0000, v145
	v_mov_b32_e32 v88, 0xff800000
	v_mov_b32_e32 v89, 0xff800000
	v_mov_b32_e32 v90, 0xff800000
	v_mov_b32_e32 v91, 0xff800000
	v_mov_b32_e32 v92, 0xff800000
	v_mov_b32_e32 v93, 0xff800000
	v_mov_b32_e32 v94, 0xff800000
	v_mov_b32_e32 v95, 0xff800000
	v_mov_b32_e32 v96, 0xff800000
	v_mov_b32_e32 v97, 0xff800000
	v_mov_b32_e32 v98, 0xff800000
	s_waitcnt lgkmcnt(8)
	v_pk_mul_f32 v[68:69], v[162:163], v[4:5]
	v_pk_fma_f32 v[68:69], v[164:165], v[6:7], v[68:69]
	v_pk_fma_f32 v[68:69], v[166:167], v[8:9], v[68:69]
	v_pk_fma_f32 v[68:69], v[168:169], v[10:11], v[68:69]
	v_pk_fma_f32 v[68:69], v[170:171], v[12:13], v[68:69]
	v_pk_fma_f32 v[68:69], v[172:173], v[14:15], v[68:69]
	v_pk_fma_f32 v[68:69], v[174:175], v[16:17], v[68:69]
	v_pk_fma_f32 v[68:69], v[176:177], v[18:19], v[68:69]
	v_pk_fma_f32 v[68:69], v[178:179], v[20:21], v[68:69]
	v_pk_fma_f32 v[68:69], v[180:181], v[22:23], v[68:69]
	v_pk_fma_f32 v[68:69], v[182:183], v[24:25], v[68:69]
	v_pk_fma_f32 v[68:69], v[184:185], v[26:27], v[68:69]
	v_pk_fma_f32 v[68:69], v[186:187], v[28:29], v[68:69]
	v_pk_fma_f32 v[68:69], v[188:189], v[30:31], v[68:69]
	v_pk_fma_f32 v[68:69], v[190:191], v[32:33], v[68:69]
	v_pk_fma_f32 v[68:69], v[192:193], v[34:35], v[68:69]
	ds_read_b128 v[4:7], v157 offset:512
	ds_read_b128 v[8:11], v157 offset:528
	ds_read_b128 v[12:15], v157 offset:576
	ds_read_b128 v[16:19], v157 offset:592
	ds_read_b128 v[20:23], v157 offset:640
	ds_read_b128 v[24:27], v157 offset:656
	ds_read_b128 v[28:31], v157 offset:704
	ds_read_b128 v[32:35], v157 offset:720
	s_waitcnt lgkmcnt(8)
	v_pk_fma_f32 v[68:69], v[194:195], v[36:37], v[68:69]
	v_pk_fma_f32 v[68:69], v[196:197], v[38:39], v[68:69]
	v_pk_fma_f32 v[68:69], v[198:199], v[40:41], v[68:69]
	v_pk_fma_f32 v[68:69], v[200:201], v[42:43], v[68:69]
	v_pk_fma_f32 v[68:69], v[202:203], v[44:45], v[68:69]
	v_pk_fma_f32 v[68:69], v[204:205], v[46:47], v[68:69]
	v_pk_fma_f32 v[68:69], v[206:207], v[48:49], v[68:69]
	v_pk_fma_f32 v[68:69], v[208:209], v[50:51], v[68:69]
	v_pk_fma_f32 v[68:69], v[210:211], v[52:53], v[68:69]
	v_pk_fma_f32 v[68:69], v[212:213], v[54:55], v[68:69]
	v_pk_fma_f32 v[68:69], v[214:215], v[56:57], v[68:69]
	v_pk_fma_f32 v[68:69], v[216:217], v[58:59], v[68:69]
	v_pk_fma_f32 v[68:69], v[218:219], v[60:61], v[68:69]
	v_pk_fma_f32 v[68:69], v[220:221], v[62:63], v[68:69]
	v_pk_fma_f32 v[68:69], v[222:223], v[64:65], v[68:69]
	v_pk_fma_f32 v[68:69], v[224:225], v[66:67], v[68:69]
	ds_read_b128 v[36:39], v157 offset:768
	ds_read_b128 v[40:43], v157 offset:784
	ds_read_b128 v[44:47], v157 offset:832
	ds_read_b128 v[48:51], v157 offset:848
	ds_read_b128 v[52:55], v157 offset:896
	ds_read_b128 v[56:59], v157 offset:912
	ds_read_b128 v[60:63], v157 offset:960
	ds_read_b128 v[64:67], v157 offset:976
	v_add_f32_e32 v84, v68, v69
	s_waitcnt lgkmcnt(8)
; #define LAS __attribute__((address_space(3)))
;     ...
;                 if (kb < j) {
;                     s = 0.f;
; #pragma unroll
;                     for (int ks = 0; ks < 8; ++ks) {
;                         const f32x4 k0 = *(const LAS f32x4*)(KM + kb * 128 + 16 * ks + 8 * h2), k1 = *(const LAS f32x4*)(KM + kb * 128 + 16 * ks + 8 * h2 + 4);
;                         const u32x4 qq = __builtin_bit_cast(u32x4, qf[ks]);
;                         s += bflo(qq.x) * k0[0] + bfhi(qq.x) * k0[1] + bflo(qq.y) * k0[2] + bfhi(qq.y) * k0[3] + bflo(qq.z) * k1[0] + bfhi(qq.z) * k1[1] + bflo(qq.w) * k1[2] + bfhi(qq.w) * k1[3];
;                     }
;                     s += __shfl_xor(s, 32);
	v_pk_mul_f32 v[68:69], v[162:163], v[4:5]
	v_pk_fma_f32 v[68:69], v[164:165], v[6:7], v[68:69]
	v_pk_fma_f32 v[68:69], v[166:167], v[8:9], v[68:69]
	v_pk_fma_f32 v[68:69], v[168:169], v[10:11], v[68:69]
	v_pk_fma_f32 v[68:69], v[170:171], v[12:13], v[68:69]
	v_pk_fma_f32 v[68:69], v[172:173], v[14:15], v[68:69]
	v_pk_fma_f32 v[68:69], v[174:175], v[16:17], v[68:69]
	v_pk_fma_f32 v[68:69], v[176:177], v[18:19], v[68:69]
	v_pk_fma_f32 v[68:69], v[178:179], v[20:21], v[68:69]
	v_pk_fma_f32 v[68:69], v[180:181], v[22:23], v[68:69]
	v_pk_fma_f32 v[68:69], v[182:183], v[24:25], v[68:69]
	v_pk_fma_f32 v[68:69], v[184:185], v[26:27], v[68:69]
	v_pk_fma_f32 v[68:69], v[186:187], v[28:29], v[68:69]
	v_pk_fma_f32 v[68:69], v[188:189], v[30:31], v[68:69]
	v_pk_fma_f32 v[68:69], v[190:191], v[32:33], v[68:69]
	v_pk_fma_f32 v[68:69], v[192:193], v[34:35], v[68:69]
	ds_read_b128 v[4:7], v157 offset:1024
	ds_read_b128 v[8:11], v157 offset:1040
	ds_read_b128 v[12:15], v157 offset:1088
	ds_read_b128 v[16:19], v157 offset:1104
	ds_read_b128 v[20:23], v157 offset:1152
	ds_read_b128 v[24:27], v157 offset:1168
	ds_read_b128 v[28:31], v157 offset:1216
	ds_read_b128 v[32:35], v157 offset:1232
	s_waitcnt lgkmcnt(8)
	v_pk_fma_f32 v[68:69], v[194:195], v[36:37], v[68:69]
	v_pk_fma_f32 v[68:69], v[196:197], v[38:39], v[68:69]
	v_pk_fma_f32 v[68:69], v[198:199], v[40:41], v[68:69]
	v_pk_fma_f32 v[68:69], v[200:201], v[42:43], v[68:69]
	v_pk_fma_f32 v[68:69], v[202:203], v[44:45], v[68:69]
	v_pk_fma_f32 v[68:69], v[204:205], v[46:47], v[68:69]
	v_pk_fma_f32 v[68:69], v[206:207], v[48:49], v[68:69]
	v_pk_fma_f32 v[68:69], v[208:209], v[50:51], v[68:69]
	v_pk_fma_f32 v[68:69], v[210:211], v[52:53], v[68:69]
	v_pk_fma_f32 v[68:69], v[212:213], v[54:55], v[68:69]
	v_pk_fma_f32 v[68:69], v[214:215], v[56:57], v[68:69]
	v_pk_fma_f32 v[68:69], v[216:217], v[58:59], v[68:69]
	v_pk_fma_f32 v[68:69], v[218:219], v[60:61], v[68:69]
	v_pk_fma_f32 v[68:69], v[220:221], v[62:63], v[68:69]
	v_pk_fma_f32 v[68:69], v[222:223], v[64:65], v[68:69]
	v_pk_fma_f32 v[68:69], v[224:225], v[66:67], v[68:69]
	ds_read_b128 v[36:39], v157 offset:1280
	ds_read_b128 v[40:43], v157 offset:1296
	ds_read_b128 v[44:47], v157 offset:1344
	ds_read_b128 v[48:51], v157 offset:1360
	ds_read_b128 v[52:55], v157 offset:1408
	ds_read_b128 v[56:59], v157 offset:1424
	ds_read_b128 v[60:63], v157 offset:1472
	ds_read_b128 v[64:67], v157 offset:1488
	v_add_f32_e32 v85, v68, v69
	s_waitcnt lgkmcnt(8)
	v_pk_mul_f32 v[68:69], v[162:163], v[4:5]
	v_pk_fma_f32 v[68:69], v[164:165], v[6:7], v[68:69]
	v_pk_fma_f32 v[68:69], v[166:167], v[8:9], v[68:69]
	v_pk_fma_f32 v[68:69], v[168:169], v[10:11], v[68:69]
	v_pk_fma_f32 v[68:69], v[170:171], v[12:13], v[68:69]
	v_pk_fma_f32 v[68:69], v[172:173], v[14:15], v[68:69]
	v_pk_fma_f32 v[68:69], v[174:175], v[16:17], v[68:69]
	v_pk_fma_f32 v[68:69], v[176:177], v[18:19], v[68:69]
	v_pk_fma_f32 v[68:69], v[178:179], v[20:21], v[68:69]
	v_pk_fma_f32 v[68:69], v[180:181], v[22:23], v[68:69]
	v_pk_fma_f32 v[68:69], v[182:183], v[24:25], v[68:69]
	v_pk_fma_f32 v[68:69], v[184:185], v[26:27], v[68:69]
	v_pk_fma_f32 v[68:69], v[186:187], v[28:29], v[68:69]
	v_pk_fma_f32 v[68:69], v[188:189], v[30:31], v[68:69]
	v_pk_fma_f32 v[68:69], v[190:191], v[32:33], v[68:69]
	v_pk_fma_f32 v[68:69], v[192:193], v[34:35], v[68:69]
	ds_read_b128 v[4:7], v157 offset:1536
	ds_read_b128 v[8:11], v157 offset:1552
	ds_read_b128 v[12:15], v157 offset:1600
	ds_read_b128 v[16:19], v157 offset:1616
	ds_read_b128 v[20:23], v157 offset:1664
	ds_read_b128 v[24:27], v157 offset:1680
	ds_read_b128 v[28:31], v157 offset:1728
	ds_read_b128 v[32:35], v157 offset:1744
	s_waitcnt lgkmcnt(8)
	v_pk_fma_f32 v[68:69], v[194:195], v[36:37], v[68:69]
	v_pk_fma_f32 v[68:69], v[196:197], v[38:39], v[68:69]
	v_pk_fma_f32 v[68:69], v[198:199], v[40:41], v[68:69]
	v_pk_fma_f32 v[68:69], v[200:201], v[42:43], v[68:69]
	v_pk_fma_f32 v[68:69], v[202:203], v[44:45], v[68:69]
	v_pk_fma_f32 v[68:69], v[204:205], v[46:47], v[68:69]
	v_pk_fma_f32 v[68:69], v[206:207], v[48:49], v[68:69]
	v_pk_fma_f32 v[68:69], v[208:209], v[50:51], v[68:69]
	v_pk_fma_f32 v[68:69], v[210:211], v[52:53], v[68:69]
	v_pk_fma_f32 v[68:69], v[212:213], v[54:55], v[68:69]
	v_pk_fma_f32 v[68:69], v[214:215], v[56:57], v[68:69]
	v_pk_fma_f32 v[68:69], v[216:217], v[58:59], v[68:69]
	v_pk_fma_f32 v[68:69], v[218:219], v[60:61], v[68:69]
	v_pk_fma_f32 v[68:69], v[220:221], v[62:63], v[68:69]
	v_pk_fma_f32 v[68:69], v[222:223], v[64:65], v[68:69]
	v_pk_fma_f32 v[68:69], v[224:225], v[66:67], v[68:69]
	ds_read_b128 v[36:39], v157 offset:1792
	ds_read_b128 v[40:43], v157 offset:1808
	ds_read_b128 v[44:47], v157 offset:1856
	ds_read_b128 v[48:51], v157 offset:1872
	ds_read_b128 v[52:55], v157 offset:1920
	ds_read_b128 v[56:59], v157 offset:1936
	ds_read_b128 v[60:63], v157 offset:1984
	ds_read_b128 v[64:67], v157 offset:2000
	v_add_f32_e32 v86, v68, v69
	s_waitcnt lgkmcnt(8)
	v_pk_mul_f32 v[68:69], v[162:163], v[4:5]
	v_pk_fma_f32 v[68:69], v[164:165], v[6:7], v[68:69]
	v_pk_fma_f32 v[68:69], v[166:167], v[8:9], v[68:69]
	v_pk_fma_f32 v[68:69], v[168:169], v[10:11], v[68:69]
	v_pk_fma_f32 v[68:69], v[170:171], v[12:13], v[68:69]
	v_pk_fma_f32 v[68:69], v[172:173], v[14:15], v[68:69]
	v_pk_fma_f32 v[68:69], v[174:175], v[16:17], v[68:69]
	v_pk_fma_f32 v[68:69], v[176:177], v[18:19], v[68:69]
	v_pk_fma_f32 v[68:69], v[178:179], v[20:21], v[68:69]
	v_pk_fma_f32 v[68:69], v[180:181], v[22:23], v[68:69]
	v_pk_fma_f32 v[68:69], v[182:183], v[24:25], v[68:69]
	v_pk_fma_f32 v[68:69], v[184:185], v[26:27], v[68:69]
	v_pk_fma_f32 v[68:69], v[186:187], v[28:29], v[68:69]
	v_pk_fma_f32 v[68:69], v[188:189], v[30:31], v[68:69]
	v_pk_fma_f32 v[68:69], v[190:191], v[32:33], v[68:69]
	v_pk_fma_f32 v[68:69], v[192:193], v[34:35], v[68:69]
	ds_read_b128 v[4:7], v157 offset:2048
	ds_read_b128 v[8:11], v157 offset:2064
	ds_read_b128 v[12:15], v157 offset:2112
	ds_read_b128 v[16:19], v157 offset:2128
	ds_read_b128 v[20:23], v157 offset:2176
	ds_read_b128 v[24:27], v157 offset:2192
	ds_read_b128 v[28:31], v157 offset:2240
	ds_read_b128 v[32:35], v157 offset:2256
	s_waitcnt lgkmcnt(8)
; #define LAS __attribute__((address_space(3)))
;     ...
;             for (int kb = 0; kb < 15; ++kb) {
;                 float s = -INFINITY;
;                 if (kb < j) {
;                     s = 0.f;
; #pragma unroll
;                     for (int ks = 0; ks < 8; ++ks) {
;                         const f32x4 k0 = *(const LAS f32x4*)(KM + kb * 128 + 16 * ks + 8 * h2), k1 = *(const LAS f32x4*)(KM + kb * 128 + 16 * ks + 8 * h2 + 4);
;                         const u32x4 qq = __builtin_bit_cast(u32x4, qf[ks]);
;                         s += bflo(qq.x) * k0[0] + bfhi(qq.x) * k0[1] + bflo(qq.y) * k0[2] + bfhi(qq.y) * k0[3] + bflo(qq.z) * k1[0] + bfhi(qq.z) * k1[1] + bflo(qq.w) * k1[2] + bfhi(qq.w) * k1[3];
;                     }
;                     s += __shfl_xor(s, 32);
	v_pk_fma_f32 v[68:69], v[194:195], v[36:37], v[68:69]
	v_pk_fma_f32 v[68:69], v[196:197], v[38:39], v[68:69]
	v_pk_fma_f32 v[68:69], v[198:199], v[40:41], v[68:69]
	v_pk_fma_f32 v[68:69], v[200:201], v[42:43], v[68:69]
	v_pk_fma_f32 v[68:69], v[202:203], v[44:45], v[68:69]
	v_pk_fma_f32 v[68:69], v[204:205], v[46:47], v[68:69]
	v_pk_fma_f32 v[68:69], v[206:207], v[48:49], v[68:69]
	v_pk_fma_f32 v[68:69], v[208:209], v[50:51], v[68:69]
	v_pk_fma_f32 v[68:69], v[210:211], v[52:53], v[68:69]
	v_pk_fma_f32 v[68:69], v[212:213], v[54:55], v[68:69]
	v_pk_fma_f32 v[68:69], v[214:215], v[56:57], v[68:69]
	v_pk_fma_f32 v[68:69], v[216:217], v[58:59], v[68:69]
	v_pk_fma_f32 v[68:69], v[218:219], v[60:61], v[68:69]
	v_pk_fma_f32 v[68:69], v[220:221], v[62:63], v[68:69]
	v_pk_fma_f32 v[68:69], v[222:223], v[64:65], v[68:69]
	v_pk_fma_f32 v[68:69], v[224:225], v[66:67], v[68:69]
	ds_read_b128 v[36:39], v157 offset:2304
	ds_read_b128 v[40:43], v157 offset:2320
	ds_read_b128 v[44:47], v157 offset:2368
	ds_read_b128 v[48:51], v157 offset:2384
	ds_read_b128 v[52:55], v157 offset:2432
	ds_read_b128 v[56:59], v157 offset:2448
	ds_read_b128 v[60:63], v157 offset:2496
	ds_read_b128 v[64:67], v157 offset:2512
	v_add_f32_e32 v87, v68, v69
	s_cmp_le_u32 s11, 4
	s_cbranch_scc1 .Lgate_dot_done
	s_waitcnt lgkmcnt(8)
	v_pk_mul_f32 v[68:69], v[162:163], v[4:5]
	v_pk_fma_f32 v[68:69], v[164:165], v[6:7], v[68:69]
	v_pk_fma_f32 v[68:69], v[166:167], v[8:9], v[68:69]
	v_pk_fma_f32 v[68:69], v[168:169], v[10:11], v[68:69]
	v_pk_fma_f32 v[68:69], v[170:171], v[12:13], v[68:69]
	v_pk_fma_f32 v[68:69], v[172:173], v[14:15], v[68:69]
	v_pk_fma_f32 v[68:69], v[174:175], v[16:17], v[68:69]
	v_pk_fma_f32 v[68:69], v[176:177], v[18:19], v[68:69]
	v_pk_fma_f32 v[68:69], v[178:179], v[20:21], v[68:69]
	v_pk_fma_f32 v[68:69], v[180:181], v[22:23], v[68:69]
	v_pk_fma_f32 v[68:69], v[182:183], v[24:25], v[68:69]
	v_pk_fma_f32 v[68:69], v[184:185], v[26:27], v[68:69]
	v_pk_fma_f32 v[68:69], v[186:187], v[28:29], v[68:69]
	v_pk_fma_f32 v[68:69], v[188:189], v[30:31], v[68:69]
	v_pk_fma_f32 v[68:69], v[190:191], v[32:33], v[68:69]
	v_pk_fma_f32 v[68:69], v[192:193], v[34:35], v[68:69]
	ds_read_b128 v[4:7], v157 offset:2560
	ds_read_b128 v[8:11], v157 offset:2576
	ds_read_b128 v[12:15], v157 offset:2624
	ds_read_b128 v[16:19], v157 offset:2640
	ds_read_b128 v[20:23], v157 offset:2688
	ds_read_b128 v[24:27], v157 offset:2704
	ds_read_b128 v[28:31], v157 offset:2752
	ds_read_b128 v[32:35], v157 offset:2768
	s_waitcnt lgkmcnt(8)
	v_pk_fma_f32 v[68:69], v[194:195], v[36:37], v[68:69]
	v_pk_fma_f32 v[68:69], v[196:197], v[38:39], v[68:69]
	v_pk_fma_f32 v[68:69], v[198:199], v[40:41], v[68:69]
	v_pk_fma_f32 v[68:69], v[200:201], v[42:43], v[68:69]
	v_pk_fma_f32 v[68:69], v[202:203], v[44:45], v[68:69]
	v_pk_fma_f32 v[68:69], v[204:205], v[46:47], v[68:69]
	v_pk_fma_f32 v[68:69], v[206:207], v[48:49], v[68:69]
	v_pk_fma_f32 v[68:69], v[208:209], v[50:51], v[68:69]
	v_pk_fma_f32 v[68:69], v[210:211], v[52:53], v[68:69]
	v_pk_fma_f32 v[68:69], v[212:213], v[54:55], v[68:69]
	v_pk_fma_f32 v[68:69], v[214:215], v[56:57], v[68:69]
	v_pk_fma_f32 v[68:69], v[216:217], v[58:59], v[68:69]
	v_pk_fma_f32 v[68:69], v[218:219], v[60:61], v[68:69]
	v_pk_fma_f32 v[68:69], v[220:221], v[62:63], v[68:69]
	v_pk_fma_f32 v[68:69], v[222:223], v[64:65], v[68:69]
	v_pk_fma_f32 v[68:69], v[224:225], v[66:67], v[68:69]
	ds_read_b128 v[36:39], v157 offset:2816
	ds_read_b128 v[40:43], v157 offset:2832
	ds_read_b128 v[44:47], v157 offset:2880
	ds_read_b128 v[48:51], v157 offset:2896
	ds_read_b128 v[52:55], v157 offset:2944
	ds_read_b128 v[56:59], v157 offset:2960
	ds_read_b128 v[60:63], v157 offset:3008
	ds_read_b128 v[64:67], v157 offset:3024
	v_add_f32_e32 v88, v68, v69
	s_cmp_le_u32 s11, 5
	s_cbranch_scc1 .Lgate_dot_done
	s_waitcnt lgkmcnt(8)
	v_pk_mul_f32 v[68:69], v[162:163], v[4:5]
	v_pk_fma_f32 v[68:69], v[164:165], v[6:7], v[68:69]
	v_pk_fma_f32 v[68:69], v[166:167], v[8:9], v[68:69]
	v_pk_fma_f32 v[68:69], v[168:169], v[10:11], v[68:69]
	v_pk_fma_f32 v[68:69], v[170:171], v[12:13], v[68:69]
	v_pk_fma_f32 v[68:69], v[172:173], v[14:15], v[68:69]
	v_pk_fma_f32 v[68:69], v[174:175], v[16:17], v[68:69]
	v_pk_fma_f32 v[68:69], v[176:177], v[18:19], v[68:69]
	v_pk_fma_f32 v[68:69], v[178:179], v[20:21], v[68:69]
	v_pk_fma_f32 v[68:69], v[180:181], v[22:23], v[68:69]
	v_pk_fma_f32 v[68:69], v[182:183], v[24:25], v[68:69]
	v_pk_fma_f32 v[68:69], v[184:185], v[26:27], v[68:69]
	v_pk_fma_f32 v[68:69], v[186:187], v[28:29], v[68:69]
	v_pk_fma_f32 v[68:69], v[188:189], v[30:31], v[68:69]
	v_pk_fma_f32 v[68:69], v[190:191], v[32:33], v[68:69]
	v_pk_fma_f32 v[68:69], v[192:193], v[34:35], v[68:69]
	ds_read_b128 v[4:7], v157 offset:3072
	ds_read_b128 v[8:11], v157 offset:3088
	ds_read_b128 v[12:15], v157 offset:3136
	ds_read_b128 v[16:19], v157 offset:3152
	ds_read_b128 v[20:23], v157 offset:3200
	ds_read_b128 v[24:27], v157 offset:3216
	ds_read_b128 v[28:31], v157 offset:3264
	ds_read_b128 v[32:35], v157 offset:3280
	s_waitcnt lgkmcnt(8)
	v_pk_fma_f32 v[68:69], v[194:195], v[36:37], v[68:69]
	v_pk_fma_f32 v[68:69], v[196:197], v[38:39], v[68:69]
	v_pk_fma_f32 v[68:69], v[198:199], v[40:41], v[68:69]
	v_pk_fma_f32 v[68:69], v[200:201], v[42:43], v[68:69]
	v_pk_fma_f32 v[68:69], v[202:203], v[44:45], v[68:69]
	v_pk_fma_f32 v[68:69], v[204:205], v[46:47], v[68:69]
	v_pk_fma_f32 v[68:69], v[206:207], v[48:49], v[68:69]
	v_pk_fma_f32 v[68:69], v[208:209], v[50:51], v[68:69]
	v_pk_fma_f32 v[68:69], v[210:211], v[52:53], v[68:69]
	v_pk_fma_f32 v[68:69], v[212:213], v[54:55], v[68:69]
	v_pk_fma_f32 v[68:69], v[214:215], v[56:57], v[68:69]
	v_pk_fma_f32 v[68:69], v[216:217], v[58:59], v[68:69]
	v_pk_fma_f32 v[68:69], v[218:219], v[60:61], v[68:69]
	v_pk_fma_f32 v[68:69], v[220:221], v[62:63], v[68:69]
	v_pk_fma_f32 v[68:69], v[222:223], v[64:65], v[68:69]
	v_pk_fma_f32 v[68:69], v[224:225], v[66:67], v[68:69]
	ds_read_b128 v[36:39], v157 offset:3328
	ds_read_b128 v[40:43], v157 offset:3344
	ds_read_b128 v[44:47], v157 offset:3392
	ds_read_b128 v[48:51], v157 offset:3408
	ds_read_b128 v[52:55], v157 offset:3456
	ds_read_b128 v[56:59], v157 offset:3472
	ds_read_b128 v[60:63], v157 offset:3520
	ds_read_b128 v[64:67], v157 offset:3536
	v_add_f32_e32 v89, v68, v69
	s_cmp_le_u32 s11, 6
	s_cbranch_scc1 .Lgate_dot_done
; #define LAS __attribute__((address_space(3)))
;     ...
;             for (int kb = 0; kb < 15; ++kb) {
;                 float s = -INFINITY;
;                 if (kb < j) {
;                     s = 0.f;
; #pragma unroll
;                     for (int ks = 0; ks < 8; ++ks) {
;                         const f32x4 k0 = *(const LAS f32x4*)(KM + kb * 128 + 16 * ks + 8 * h2), k1 = *(const LAS f32x4*)(KM + kb * 128 + 16 * ks + 8 * h2 + 4);
;                         const u32x4 qq = __builtin_bit_cast(u32x4, qf[ks]);
;                         s += bflo(qq.x) * k0[0] + bfhi(qq.x) * k0[1] + bflo(qq.y) * k0[2] + bfhi(qq.y) * k0[3] + bflo(qq.z) * k1[0] + bfhi(qq.z) * k1[1] + bflo(qq.w) * k1[2] + bfhi(qq.w) * k1[3];
;                     }
;                     s += __shfl_xor(s, 32);
	s_waitcnt lgkmcnt(8)
	v_pk_mul_f32 v[68:69], v[162:163], v[4:5]
	v_pk_fma_f32 v[68:69], v[164:165], v[6:7], v[68:69]
	v_pk_fma_f32 v[68:69], v[166:167], v[8:9], v[68:69]
	v_pk_fma_f32 v[68:69], v[168:169], v[10:11], v[68:69]
	v_pk_fma_f32 v[68:69], v[170:171], v[12:13], v[68:69]
	v_pk_fma_f32 v[68:69], v[172:173], v[14:15], v[68:69]
	v_pk_fma_f32 v[68:69], v[174:175], v[16:17], v[68:69]
	v_pk_fma_f32 v[68:69], v[176:177], v[18:19], v[68:69]
	v_pk_fma_f32 v[68:69], v[178:179], v[20:21], v[68:69]
	v_pk_fma_f32 v[68:69], v[180:181], v[22:23], v[68:69]
	v_pk_fma_f32 v[68:69], v[182:183], v[24:25], v[68:69]
	v_pk_fma_f32 v[68:69], v[184:185], v[26:27], v[68:69]
	v_pk_fma_f32 v[68:69], v[186:187], v[28:29], v[68:69]
	v_pk_fma_f32 v[68:69], v[188:189], v[30:31], v[68:69]
	v_pk_fma_f32 v[68:69], v[190:191], v[32:33], v[68:69]
	v_pk_fma_f32 v[68:69], v[192:193], v[34:35], v[68:69]
	ds_read_b128 v[4:7], v157 offset:3584
	ds_read_b128 v[8:11], v157 offset:3600
	ds_read_b128 v[12:15], v157 offset:3648
	ds_read_b128 v[16:19], v157 offset:3664
	ds_read_b128 v[20:23], v157 offset:3712
	ds_read_b128 v[24:27], v157 offset:3728
	ds_read_b128 v[28:31], v157 offset:3776
	ds_read_b128 v[32:35], v157 offset:3792
	s_waitcnt lgkmcnt(8)
	v_pk_fma_f32 v[68:69], v[194:195], v[36:37], v[68:69]
	v_pk_fma_f32 v[68:69], v[196:197], v[38:39], v[68:69]
	v_pk_fma_f32 v[68:69], v[198:199], v[40:41], v[68:69]
	v_pk_fma_f32 v[68:69], v[200:201], v[42:43], v[68:69]
	v_pk_fma_f32 v[68:69], v[202:203], v[44:45], v[68:69]
	v_pk_fma_f32 v[68:69], v[204:205], v[46:47], v[68:69]
	v_pk_fma_f32 v[68:69], v[206:207], v[48:49], v[68:69]
	v_pk_fma_f32 v[68:69], v[208:209], v[50:51], v[68:69]
	v_pk_fma_f32 v[68:69], v[210:211], v[52:53], v[68:69]
	v_pk_fma_f32 v[68:69], v[212:213], v[54:55], v[68:69]
	v_pk_fma_f32 v[68:69], v[214:215], v[56:57], v[68:69]
	v_pk_fma_f32 v[68:69], v[216:217], v[58:59], v[68:69]
	v_pk_fma_f32 v[68:69], v[218:219], v[60:61], v[68:69]
	v_pk_fma_f32 v[68:69], v[220:221], v[62:63], v[68:69]
	v_pk_fma_f32 v[68:69], v[222:223], v[64:65], v[68:69]
	v_pk_fma_f32 v[68:69], v[224:225], v[66:67], v[68:69]
	ds_read_b128 v[36:39], v157 offset:3840
	ds_read_b128 v[40:43], v157 offset:3856
	ds_read_b128 v[44:47], v157 offset:3904
	ds_read_b128 v[48:51], v157 offset:3920
	ds_read_b128 v[52:55], v157 offset:3968
	ds_read_b128 v[56:59], v157 offset:3984
	ds_read_b128 v[60:63], v157 offset:4032
	ds_read_b128 v[64:67], v157 offset:4048
	v_add_f32_e32 v90, v68, v69
	s_cmp_le_u32 s11, 7
	s_cbranch_scc1 .Lgate_dot_done
	s_waitcnt lgkmcnt(8)
	v_pk_mul_f32 v[68:69], v[162:163], v[4:5]
	v_pk_fma_f32 v[68:69], v[164:165], v[6:7], v[68:69]
	v_pk_fma_f32 v[68:69], v[166:167], v[8:9], v[68:69]
	v_pk_fma_f32 v[68:69], v[168:169], v[10:11], v[68:69]
	v_pk_fma_f32 v[68:69], v[170:171], v[12:13], v[68:69]
	v_pk_fma_f32 v[68:69], v[172:173], v[14:15], v[68:69]
	v_pk_fma_f32 v[68:69], v[174:175], v[16:17], v[68:69]
	v_pk_fma_f32 v[68:69], v[176:177], v[18:19], v[68:69]
	v_pk_fma_f32 v[68:69], v[178:179], v[20:21], v[68:69]
	v_pk_fma_f32 v[68:69], v[180:181], v[22:23], v[68:69]
	v_pk_fma_f32 v[68:69], v[182:183], v[24:25], v[68:69]
	v_pk_fma_f32 v[68:69], v[184:185], v[26:27], v[68:69]
	v_pk_fma_f32 v[68:69], v[186:187], v[28:29], v[68:69]
	v_pk_fma_f32 v[68:69], v[188:189], v[30:31], v[68:69]
	v_pk_fma_f32 v[68:69], v[190:191], v[32:33], v[68:69]
	v_pk_fma_f32 v[68:69], v[192:193], v[34:35], v[68:69]
	ds_read_b128 v[4:7], v157 offset:4096
	ds_read_b128 v[8:11], v157 offset:4112
	ds_read_b128 v[12:15], v157 offset:4160
	ds_read_b128 v[16:19], v157 offset:4176
	ds_read_b128 v[20:23], v157 offset:4224
	ds_read_b128 v[24:27], v157 offset:4240
	ds_read_b128 v[28:31], v157 offset:4288
	ds_read_b128 v[32:35], v157 offset:4304
	s_waitcnt lgkmcnt(8)
	v_pk_fma_f32 v[68:69], v[194:195], v[36:37], v[68:69]
	v_pk_fma_f32 v[68:69], v[196:197], v[38:39], v[68:69]
	v_pk_fma_f32 v[68:69], v[198:199], v[40:41], v[68:69]
	v_pk_fma_f32 v[68:69], v[200:201], v[42:43], v[68:69]
	v_pk_fma_f32 v[68:69], v[202:203], v[44:45], v[68:69]
	v_pk_fma_f32 v[68:69], v[204:205], v[46:47], v[68:69]
	v_pk_fma_f32 v[68:69], v[206:207], v[48:49], v[68:69]
	v_pk_fma_f32 v[68:69], v[208:209], v[50:51], v[68:69]
	v_pk_fma_f32 v[68:69], v[210:211], v[52:53], v[68:69]
	v_pk_fma_f32 v[68:69], v[212:213], v[54:55], v[68:69]
	v_pk_fma_f32 v[68:69], v[214:215], v[56:57], v[68:69]
	v_pk_fma_f32 v[68:69], v[216:217], v[58:59], v[68:69]
	v_pk_fma_f32 v[68:69], v[218:219], v[60:61], v[68:69]
	v_pk_fma_f32 v[68:69], v[220:221], v[62:63], v[68:69]
	v_pk_fma_f32 v[68:69], v[222:223], v[64:65], v[68:69]
	v_pk_fma_f32 v[68:69], v[224:225], v[66:67], v[68:69]
	ds_read_b128 v[36:39], v157 offset:4352
	ds_read_b128 v[40:43], v157 offset:4368
	ds_read_b128 v[44:47], v157 offset:4416
	ds_read_b128 v[48:51], v157 offset:4432
	ds_read_b128 v[52:55], v157 offset:4480
	ds_read_b128 v[56:59], v157 offset:4496
	ds_read_b128 v[60:63], v157 offset:4544
	ds_read_b128 v[64:67], v157 offset:4560
	v_add_f32_e32 v91, v68, v69
	s_cmp_le_u32 s11, 8
	s_cbranch_scc1 .Lgate_dot_done
; #define LAS __attribute__((address_space(3)))
;     ...
;             for (int kb = 0; kb < 15; ++kb) {
;                 float s = -INFINITY;
;                 if (kb < j) {
;                     s = 0.f;
; #pragma unroll
;                     for (int ks = 0; ks < 8; ++ks) {
;                         const f32x4 k0 = *(const LAS f32x4*)(KM + kb * 128 + 16 * ks + 8 * h2), k1 = *(const LAS f32x4*)(KM + kb * 128 + 16 * ks + 8 * h2 + 4);
;                         const u32x4 qq = __builtin_bit_cast(u32x4, qf[ks]);
;                         s += bflo(qq.x) * k0[0] + bfhi(qq.x) * k0[1] + bflo(qq.y) * k0[2] + bfhi(qq.y) * k0[3] + bflo(qq.z) * k1[0] + bfhi(qq.z) * k1[1] + bflo(qq.w) * k1[2] + bfhi(qq.w) * k1[3];
;                     }
;                     s += __shfl_xor(s, 32);
	s_waitcnt lgkmcnt(8)
	v_pk_mul_f32 v[68:69], v[162:163], v[4:5]
	v_pk_fma_f32 v[68:69], v[164:165], v[6:7], v[68:69]
	v_pk_fma_f32 v[68:69], v[166:167], v[8:9], v[68:69]
	v_pk_fma_f32 v[68:69], v[168:169], v[10:11], v[68:69]
	v_pk_fma_f32 v[68:69], v[170:171], v[12:13], v[68:69]
	v_pk_fma_f32 v[68:69], v[172:173], v[14:15], v[68:69]
	v_pk_fma_f32 v[68:69], v[174:175], v[16:17], v[68:69]
	v_pk_fma_f32 v[68:69], v[176:177], v[18:19], v[68:69]
	v_pk_fma_f32 v[68:69], v[178:179], v[20:21], v[68:69]
	v_pk_fma_f32 v[68:69], v[180:181], v[22:23], v[68:69]
	v_pk_fma_f32 v[68:69], v[182:183], v[24:25], v[68:69]
	v_pk_fma_f32 v[68:69], v[184:185], v[26:27], v[68:69]
	v_pk_fma_f32 v[68:69], v[186:187], v[28:29], v[68:69]
	v_pk_fma_f32 v[68:69], v[188:189], v[30:31], v[68:69]
	v_pk_fma_f32 v[68:69], v[190:191], v[32:33], v[68:69]
	v_pk_fma_f32 v[68:69], v[192:193], v[34:35], v[68:69]
	ds_read_b128 v[4:7], v157 offset:4608
	ds_read_b128 v[8:11], v157 offset:4624
	ds_read_b128 v[12:15], v157 offset:4672
	ds_read_b128 v[16:19], v157 offset:4688
	ds_read_b128 v[20:23], v157 offset:4736
	ds_read_b128 v[24:27], v157 offset:4752
	ds_read_b128 v[28:31], v157 offset:4800
	ds_read_b128 v[32:35], v157 offset:4816
	s_waitcnt lgkmcnt(8)
	v_pk_fma_f32 v[68:69], v[194:195], v[36:37], v[68:69]
	v_pk_fma_f32 v[68:69], v[196:197], v[38:39], v[68:69]
	v_pk_fma_f32 v[68:69], v[198:199], v[40:41], v[68:69]
	v_pk_fma_f32 v[68:69], v[200:201], v[42:43], v[68:69]
	v_pk_fma_f32 v[68:69], v[202:203], v[44:45], v[68:69]
	v_pk_fma_f32 v[68:69], v[204:205], v[46:47], v[68:69]
	v_pk_fma_f32 v[68:69], v[206:207], v[48:49], v[68:69]
	v_pk_fma_f32 v[68:69], v[208:209], v[50:51], v[68:69]
	v_pk_fma_f32 v[68:69], v[210:211], v[52:53], v[68:69]
	v_pk_fma_f32 v[68:69], v[212:213], v[54:55], v[68:69]
	v_pk_fma_f32 v[68:69], v[214:215], v[56:57], v[68:69]
	v_pk_fma_f32 v[68:69], v[216:217], v[58:59], v[68:69]
	v_pk_fma_f32 v[68:69], v[218:219], v[60:61], v[68:69]
	v_pk_fma_f32 v[68:69], v[220:221], v[62:63], v[68:69]
	v_pk_fma_f32 v[68:69], v[222:223], v[64:65], v[68:69]
	v_pk_fma_f32 v[68:69], v[224:225], v[66:67], v[68:69]
	ds_read_b128 v[36:39], v157 offset:4864
	ds_read_b128 v[40:43], v157 offset:4880
	ds_read_b128 v[44:47], v157 offset:4928
	ds_read_b128 v[48:51], v157 offset:4944
	ds_read_b128 v[52:55], v157 offset:4992
	ds_read_b128 v[56:59], v157 offset:5008
	ds_read_b128 v[60:63], v157 offset:5056
	ds_read_b128 v[64:67], v157 offset:5072
	v_add_f32_e32 v92, v68, v69
	s_cmp_le_u32 s11, 9
	s_cbranch_scc1 .Lgate_dot_done
	s_waitcnt lgkmcnt(8)
	v_pk_mul_f32 v[68:69], v[162:163], v[4:5]
	v_pk_fma_f32 v[68:69], v[164:165], v[6:7], v[68:69]
	v_pk_fma_f32 v[68:69], v[166:167], v[8:9], v[68:69]
	v_pk_fma_f32 v[68:69], v[168:169], v[10:11], v[68:69]
	v_pk_fma_f32 v[68:69], v[170:171], v[12:13], v[68:69]
	v_pk_fma_f32 v[68:69], v[172:173], v[14:15], v[68:69]
	v_pk_fma_f32 v[68:69], v[174:175], v[16:17], v[68:69]
	v_pk_fma_f32 v[68:69], v[176:177], v[18:19], v[68:69]
	v_pk_fma_f32 v[68:69], v[178:179], v[20:21], v[68:69]
	v_pk_fma_f32 v[68:69], v[180:181], v[22:23], v[68:69]
	v_pk_fma_f32 v[68:69], v[182:183], v[24:25], v[68:69]
	v_pk_fma_f32 v[68:69], v[184:185], v[26:27], v[68:69]
	v_pk_fma_f32 v[68:69], v[186:187], v[28:29], v[68:69]
	v_pk_fma_f32 v[68:69], v[188:189], v[30:31], v[68:69]
	v_pk_fma_f32 v[68:69], v[190:191], v[32:33], v[68:69]
	v_pk_fma_f32 v[68:69], v[192:193], v[34:35], v[68:69]
	ds_read_b128 v[4:7], v157 offset:5120
	ds_read_b128 v[8:11], v157 offset:5136
	ds_read_b128 v[12:15], v157 offset:5184
	ds_read_b128 v[16:19], v157 offset:5200
	ds_read_b128 v[20:23], v157 offset:5248
	ds_read_b128 v[24:27], v157 offset:5264
	ds_read_b128 v[28:31], v157 offset:5312
	ds_read_b128 v[32:35], v157 offset:5328
	s_waitcnt lgkmcnt(8)
	v_pk_fma_f32 v[68:69], v[194:195], v[36:37], v[68:69]
	v_pk_fma_f32 v[68:69], v[196:197], v[38:39], v[68:69]
	v_pk_fma_f32 v[68:69], v[198:199], v[40:41], v[68:69]
	v_pk_fma_f32 v[68:69], v[200:201], v[42:43], v[68:69]
	v_pk_fma_f32 v[68:69], v[202:203], v[44:45], v[68:69]
	v_pk_fma_f32 v[68:69], v[204:205], v[46:47], v[68:69]
	v_pk_fma_f32 v[68:69], v[206:207], v[48:49], v[68:69]
	v_pk_fma_f32 v[68:69], v[208:209], v[50:51], v[68:69]
	v_pk_fma_f32 v[68:69], v[210:211], v[52:53], v[68:69]
	v_pk_fma_f32 v[68:69], v[212:213], v[54:55], v[68:69]
	v_pk_fma_f32 v[68:69], v[214:215], v[56:57], v[68:69]
	v_pk_fma_f32 v[68:69], v[216:217], v[58:59], v[68:69]
	v_pk_fma_f32 v[68:69], v[218:219], v[60:61], v[68:69]
	v_pk_fma_f32 v[68:69], v[220:221], v[62:63], v[68:69]
	v_pk_fma_f32 v[68:69], v[222:223], v[64:65], v[68:69]
	v_pk_fma_f32 v[68:69], v[224:225], v[66:67], v[68:69]
	ds_read_b128 v[36:39], v157 offset:5376
	ds_read_b128 v[40:43], v157 offset:5392
	ds_read_b128 v[44:47], v157 offset:5440
	ds_read_b128 v[48:51], v157 offset:5456
	ds_read_b128 v[52:55], v157 offset:5504
	ds_read_b128 v[56:59], v157 offset:5520
	ds_read_b128 v[60:63], v157 offset:5568
	ds_read_b128 v[64:67], v157 offset:5584
	v_add_f32_e32 v93, v68, v69
	s_cmp_le_u32 s11, 10
	s_cbranch_scc1 .Lgate_dot_done
; #define LAS __attribute__((address_space(3)))
;     ...
;             for (int kb = 0; kb < 15; ++kb) {
;                 float s = -INFINITY;
;                 if (kb < j) {
;                     s = 0.f;
; #pragma unroll
;                     for (int ks = 0; ks < 8; ++ks) {
;                         const f32x4 k0 = *(const LAS f32x4*)(KM + kb * 128 + 16 * ks + 8 * h2), k1 = *(const LAS f32x4*)(KM + kb * 128 + 16 * ks + 8 * h2 + 4);
;                         const u32x4 qq = __builtin_bit_cast(u32x4, qf[ks]);
;                         s += bflo(qq.x) * k0[0] + bfhi(qq.x) * k0[1] + bflo(qq.y) * k0[2] + bfhi(qq.y) * k0[3] + bflo(qq.z) * k1[0] + bfhi(qq.z) * k1[1] + bflo(qq.w) * k1[2] + bfhi(qq.w) * k1[3];
;                     }
;                     s += __shfl_xor(s, 32);
	s_waitcnt lgkmcnt(8)
	v_pk_mul_f32 v[68:69], v[162:163], v[4:5]
	v_pk_fma_f32 v[68:69], v[164:165], v[6:7], v[68:69]
	v_pk_fma_f32 v[68:69], v[166:167], v[8:9], v[68:69]
	v_pk_fma_f32 v[68:69], v[168:169], v[10:11], v[68:69]
	v_pk_fma_f32 v[68:69], v[170:171], v[12:13], v[68:69]
	v_pk_fma_f32 v[68:69], v[172:173], v[14:15], v[68:69]
	v_pk_fma_f32 v[68:69], v[174:175], v[16:17], v[68:69]
	v_pk_fma_f32 v[68:69], v[176:177], v[18:19], v[68:69]
	v_pk_fma_f32 v[68:69], v[178:179], v[20:21], v[68:69]
	v_pk_fma_f32 v[68:69], v[180:181], v[22:23], v[68:69]
	v_pk_fma_f32 v[68:69], v[182:183], v[24:25], v[68:69]
	v_pk_fma_f32 v[68:69], v[184:185], v[26:27], v[68:69]
	v_pk_fma_f32 v[68:69], v[186:187], v[28:29], v[68:69]
	v_pk_fma_f32 v[68:69], v[188:189], v[30:31], v[68:69]
	v_pk_fma_f32 v[68:69], v[190:191], v[32:33], v[68:69]
	v_pk_fma_f32 v[68:69], v[192:193], v[34:35], v[68:69]
	ds_read_b128 v[4:7], v157 offset:5632
	ds_read_b128 v[8:11], v157 offset:5648
	ds_read_b128 v[12:15], v157 offset:5696
	ds_read_b128 v[16:19], v157 offset:5712
	ds_read_b128 v[20:23], v157 offset:5760
	ds_read_b128 v[24:27], v157 offset:5776
	ds_read_b128 v[28:31], v157 offset:5824
	ds_read_b128 v[32:35], v157 offset:5840
	s_waitcnt lgkmcnt(8)
	v_pk_fma_f32 v[68:69], v[194:195], v[36:37], v[68:69]
	v_pk_fma_f32 v[68:69], v[196:197], v[38:39], v[68:69]
	v_pk_fma_f32 v[68:69], v[198:199], v[40:41], v[68:69]
	v_pk_fma_f32 v[68:69], v[200:201], v[42:43], v[68:69]
	v_pk_fma_f32 v[68:69], v[202:203], v[44:45], v[68:69]
	v_pk_fma_f32 v[68:69], v[204:205], v[46:47], v[68:69]
	v_pk_fma_f32 v[68:69], v[206:207], v[48:49], v[68:69]
	v_pk_fma_f32 v[68:69], v[208:209], v[50:51], v[68:69]
	v_pk_fma_f32 v[68:69], v[210:211], v[52:53], v[68:69]
	v_pk_fma_f32 v[68:69], v[212:213], v[54:55], v[68:69]
	v_pk_fma_f32 v[68:69], v[214:215], v[56:57], v[68:69]
	v_pk_fma_f32 v[68:69], v[216:217], v[58:59], v[68:69]
	v_pk_fma_f32 v[68:69], v[218:219], v[60:61], v[68:69]
	v_pk_fma_f32 v[68:69], v[220:221], v[62:63], v[68:69]
	v_pk_fma_f32 v[68:69], v[222:223], v[64:65], v[68:69]
	v_pk_fma_f32 v[68:69], v[224:225], v[66:67], v[68:69]
	ds_read_b128 v[36:39], v157 offset:5888
	ds_read_b128 v[40:43], v157 offset:5904
	ds_read_b128 v[44:47], v157 offset:5952
	ds_read_b128 v[48:51], v157 offset:5968
	ds_read_b128 v[52:55], v157 offset:6016
	ds_read_b128 v[56:59], v157 offset:6032
	ds_read_b128 v[60:63], v157 offset:6080
	ds_read_b128 v[64:67], v157 offset:6096
	v_add_f32_e32 v94, v68, v69
	s_cmp_le_u32 s11, 11
	s_cbranch_scc1 .Lgate_dot_done
	s_waitcnt lgkmcnt(8)
	v_pk_mul_f32 v[68:69], v[162:163], v[4:5]
	v_pk_fma_f32 v[68:69], v[164:165], v[6:7], v[68:69]
	v_pk_fma_f32 v[68:69], v[166:167], v[8:9], v[68:69]
	v_pk_fma_f32 v[68:69], v[168:169], v[10:11], v[68:69]
	v_pk_fma_f32 v[68:69], v[170:171], v[12:13], v[68:69]
	v_pk_fma_f32 v[68:69], v[172:173], v[14:15], v[68:69]
	v_pk_fma_f32 v[68:69], v[174:175], v[16:17], v[68:69]
	v_pk_fma_f32 v[68:69], v[176:177], v[18:19], v[68:69]
	v_pk_fma_f32 v[68:69], v[178:179], v[20:21], v[68:69]
	v_pk_fma_f32 v[68:69], v[180:181], v[22:23], v[68:69]
	v_pk_fma_f32 v[68:69], v[182:183], v[24:25], v[68:69]
	v_pk_fma_f32 v[68:69], v[184:185], v[26:27], v[68:69]
	v_pk_fma_f32 v[68:69], v[186:187], v[28:29], v[68:69]
	v_pk_fma_f32 v[68:69], v[188:189], v[30:31], v[68:69]
	v_pk_fma_f32 v[68:69], v[190:191], v[32:33], v[68:69]
	v_pk_fma_f32 v[68:69], v[192:193], v[34:35], v[68:69]
	ds_read_b128 v[4:7], v157 offset:6144
	ds_read_b128 v[8:11], v157 offset:6160
	ds_read_b128 v[12:15], v157 offset:6208
	ds_read_b128 v[16:19], v157 offset:6224
	ds_read_b128 v[20:23], v157 offset:6272
	ds_read_b128 v[24:27], v157 offset:6288
	ds_read_b128 v[28:31], v157 offset:6336
	ds_read_b128 v[32:35], v157 offset:6352
	s_waitcnt lgkmcnt(8)
	v_pk_fma_f32 v[68:69], v[194:195], v[36:37], v[68:69]
	v_pk_fma_f32 v[68:69], v[196:197], v[38:39], v[68:69]
	v_pk_fma_f32 v[68:69], v[198:199], v[40:41], v[68:69]
	v_pk_fma_f32 v[68:69], v[200:201], v[42:43], v[68:69]
	v_pk_fma_f32 v[68:69], v[202:203], v[44:45], v[68:69]
	v_pk_fma_f32 v[68:69], v[204:205], v[46:47], v[68:69]
	v_pk_fma_f32 v[68:69], v[206:207], v[48:49], v[68:69]
	v_pk_fma_f32 v[68:69], v[208:209], v[50:51], v[68:69]
	v_pk_fma_f32 v[68:69], v[210:211], v[52:53], v[68:69]
	v_pk_fma_f32 v[68:69], v[212:213], v[54:55], v[68:69]
	v_pk_fma_f32 v[68:69], v[214:215], v[56:57], v[68:69]
	v_pk_fma_f32 v[68:69], v[216:217], v[58:59], v[68:69]
	v_pk_fma_f32 v[68:69], v[218:219], v[60:61], v[68:69]
	v_pk_fma_f32 v[68:69], v[220:221], v[62:63], v[68:69]
	v_pk_fma_f32 v[68:69], v[222:223], v[64:65], v[68:69]
	v_pk_fma_f32 v[68:69], v[224:225], v[66:67], v[68:69]
	ds_read_b128 v[36:39], v157 offset:6400
	ds_read_b128 v[40:43], v157 offset:6416
	ds_read_b128 v[44:47], v157 offset:6464
	ds_read_b128 v[48:51], v157 offset:6480
	ds_read_b128 v[52:55], v157 offset:6528
	ds_read_b128 v[56:59], v157 offset:6544
	ds_read_b128 v[60:63], v157 offset:6592
	ds_read_b128 v[64:67], v157 offset:6608
	v_add_f32_e32 v95, v68, v69
	s_cmp_le_u32 s11, 12
	s_cbranch_scc1 .Lgate_dot_done
; #define LAS __attribute__((address_space(3)))
;     ...
;             for (int kb = 0; kb < 15; ++kb) {
;                 float s = -INFINITY;
;                 if (kb < j) {
;                     s = 0.f;
; #pragma unroll
;                     for (int ks = 0; ks < 8; ++ks) {
;                         const f32x4 k0 = *(const LAS f32x4*)(KM + kb * 128 + 16 * ks + 8 * h2), k1 = *(const LAS f32x4*)(KM + kb * 128 + 16 * ks + 8 * h2 + 4);
;                         const u32x4 qq = __builtin_bit_cast(u32x4, qf[ks]);
;                         s += bflo(qq.x) * k0[0] + bfhi(qq.x) * k0[1] + bflo(qq.y) * k0[2] + bfhi(qq.y) * k0[3] + bflo(qq.z) * k1[0] + bfhi(qq.z) * k1[1] + bflo(qq.w) * k1[2] + bfhi(qq.w) * k1[3];
;                     }
;                     s += __shfl_xor(s, 32);
	s_waitcnt lgkmcnt(8)
	v_pk_mul_f32 v[68:69], v[162:163], v[4:5]
	v_pk_fma_f32 v[68:69], v[164:165], v[6:7], v[68:69]
	v_pk_fma_f32 v[68:69], v[166:167], v[8:9], v[68:69]
	v_pk_fma_f32 v[68:69], v[168:169], v[10:11], v[68:69]
	v_pk_fma_f32 v[68:69], v[170:171], v[12:13], v[68:69]
	v_pk_fma_f32 v[68:69], v[172:173], v[14:15], v[68:69]
	v_pk_fma_f32 v[68:69], v[174:175], v[16:17], v[68:69]
	v_pk_fma_f32 v[68:69], v[176:177], v[18:19], v[68:69]
	v_pk_fma_f32 v[68:69], v[178:179], v[20:21], v[68:69]
	v_pk_fma_f32 v[68:69], v[180:181], v[22:23], v[68:69]
	v_pk_fma_f32 v[68:69], v[182:183], v[24:25], v[68:69]
	v_pk_fma_f32 v[68:69], v[184:185], v[26:27], v[68:69]
	v_pk_fma_f32 v[68:69], v[186:187], v[28:29], v[68:69]
	v_pk_fma_f32 v[68:69], v[188:189], v[30:31], v[68:69]
	v_pk_fma_f32 v[68:69], v[190:191], v[32:33], v[68:69]
	v_pk_fma_f32 v[68:69], v[192:193], v[34:35], v[68:69]
	ds_read_b128 v[4:7], v157 offset:6656
	ds_read_b128 v[8:11], v157 offset:6672
	ds_read_b128 v[12:15], v157 offset:6720
	ds_read_b128 v[16:19], v157 offset:6736
	ds_read_b128 v[20:23], v157 offset:6784
	ds_read_b128 v[24:27], v157 offset:6800
	ds_read_b128 v[28:31], v157 offset:6848
	ds_read_b128 v[32:35], v157 offset:6864
	s_waitcnt lgkmcnt(8)
	v_pk_fma_f32 v[68:69], v[194:195], v[36:37], v[68:69]
	v_pk_fma_f32 v[68:69], v[196:197], v[38:39], v[68:69]
	v_pk_fma_f32 v[68:69], v[198:199], v[40:41], v[68:69]
	v_pk_fma_f32 v[68:69], v[200:201], v[42:43], v[68:69]
	v_pk_fma_f32 v[68:69], v[202:203], v[44:45], v[68:69]
	v_pk_fma_f32 v[68:69], v[204:205], v[46:47], v[68:69]
	v_pk_fma_f32 v[68:69], v[206:207], v[48:49], v[68:69]
	v_pk_fma_f32 v[68:69], v[208:209], v[50:51], v[68:69]
	v_pk_fma_f32 v[68:69], v[210:211], v[52:53], v[68:69]
	v_pk_fma_f32 v[68:69], v[212:213], v[54:55], v[68:69]
	v_pk_fma_f32 v[68:69], v[214:215], v[56:57], v[68:69]
	v_pk_fma_f32 v[68:69], v[216:217], v[58:59], v[68:69]
	v_pk_fma_f32 v[68:69], v[218:219], v[60:61], v[68:69]
	v_pk_fma_f32 v[68:69], v[220:221], v[62:63], v[68:69]
	v_pk_fma_f32 v[68:69], v[222:223], v[64:65], v[68:69]
	v_pk_fma_f32 v[68:69], v[224:225], v[66:67], v[68:69]
	ds_read_b128 v[36:39], v157 offset:6912
	ds_read_b128 v[40:43], v157 offset:6928
	ds_read_b128 v[44:47], v157 offset:6976
	ds_read_b128 v[48:51], v157 offset:6992
	ds_read_b128 v[52:55], v157 offset:7040
	ds_read_b128 v[56:59], v157 offset:7056
	ds_read_b128 v[60:63], v157 offset:7104
	ds_read_b128 v[64:67], v157 offset:7120
	v_add_f32_e32 v96, v68, v69
	s_cmp_le_u32 s11, 13
	s_cbranch_scc1 .Lgate_dot_done
	s_waitcnt lgkmcnt(8)
	v_pk_mul_f32 v[68:69], v[162:163], v[4:5]
	v_pk_fma_f32 v[68:69], v[164:165], v[6:7], v[68:69]
	v_pk_fma_f32 v[68:69], v[166:167], v[8:9], v[68:69]
	v_pk_fma_f32 v[68:69], v[168:169], v[10:11], v[68:69]
	v_pk_fma_f32 v[68:69], v[170:171], v[12:13], v[68:69]
	v_pk_fma_f32 v[68:69], v[172:173], v[14:15], v[68:69]
	v_pk_fma_f32 v[68:69], v[174:175], v[16:17], v[68:69]
	v_pk_fma_f32 v[68:69], v[176:177], v[18:19], v[68:69]
	v_pk_fma_f32 v[68:69], v[178:179], v[20:21], v[68:69]
	v_pk_fma_f32 v[68:69], v[180:181], v[22:23], v[68:69]
	v_pk_fma_f32 v[68:69], v[182:183], v[24:25], v[68:69]
	v_pk_fma_f32 v[68:69], v[184:185], v[26:27], v[68:69]
	v_pk_fma_f32 v[68:69], v[186:187], v[28:29], v[68:69]
	v_pk_fma_f32 v[68:69], v[188:189], v[30:31], v[68:69]
	v_pk_fma_f32 v[68:69], v[190:191], v[32:33], v[68:69]
	v_pk_fma_f32 v[68:69], v[192:193], v[34:35], v[68:69]
	ds_read_b128 v[4:7], v157 offset:7168
	ds_read_b128 v[8:11], v157 offset:7184
	ds_read_b128 v[12:15], v157 offset:7232
	ds_read_b128 v[16:19], v157 offset:7248
	ds_read_b128 v[20:23], v157 offset:7296
	ds_read_b128 v[24:27], v157 offset:7312
	ds_read_b128 v[28:31], v157 offset:7360
	ds_read_b128 v[32:35], v157 offset:7376
	s_waitcnt lgkmcnt(8)
	v_pk_fma_f32 v[68:69], v[194:195], v[36:37], v[68:69]
	v_pk_fma_f32 v[68:69], v[196:197], v[38:39], v[68:69]
	v_pk_fma_f32 v[68:69], v[198:199], v[40:41], v[68:69]
	v_pk_fma_f32 v[68:69], v[200:201], v[42:43], v[68:69]
	v_pk_fma_f32 v[68:69], v[202:203], v[44:45], v[68:69]
	v_pk_fma_f32 v[68:69], v[204:205], v[46:47], v[68:69]
	v_pk_fma_f32 v[68:69], v[206:207], v[48:49], v[68:69]
	v_pk_fma_f32 v[68:69], v[208:209], v[50:51], v[68:69]
	v_pk_fma_f32 v[68:69], v[210:211], v[52:53], v[68:69]
	v_pk_fma_f32 v[68:69], v[212:213], v[54:55], v[68:69]
	v_pk_fma_f32 v[68:69], v[214:215], v[56:57], v[68:69]
	v_pk_fma_f32 v[68:69], v[216:217], v[58:59], v[68:69]
	v_pk_fma_f32 v[68:69], v[218:219], v[60:61], v[68:69]
	v_pk_fma_f32 v[68:69], v[220:221], v[62:63], v[68:69]
	v_pk_fma_f32 v[68:69], v[222:223], v[64:65], v[68:69]
	v_pk_fma_f32 v[68:69], v[224:225], v[66:67], v[68:69]
	ds_read_b128 v[36:39], v157 offset:7424
	ds_read_b128 v[40:43], v157 offset:7440
	ds_read_b128 v[44:47], v157 offset:7488
	ds_read_b128 v[48:51], v157 offset:7504
	ds_read_b128 v[52:55], v157 offset:7552
	ds_read_b128 v[56:59], v157 offset:7568
	ds_read_b128 v[60:63], v157 offset:7616
	ds_read_b128 v[64:67], v157 offset:7632
	v_add_f32_e32 v97, v68, v69
	s_cmp_le_u32 s11, 14
	s_cbranch_scc1 .Lgate_dot_done
	s_waitcnt lgkmcnt(8)
	v_pk_mul_f32 v[68:69], v[162:163], v[4:5]
	v_pk_fma_f32 v[68:69], v[164:165], v[6:7], v[68:69]
	v_pk_fma_f32 v[68:69], v[166:167], v[8:9], v[68:69]
	v_pk_fma_f32 v[68:69], v[168:169], v[10:11], v[68:69]
	v_pk_fma_f32 v[68:69], v[170:171], v[12:13], v[68:69]
	v_pk_fma_f32 v[68:69], v[172:173], v[14:15], v[68:69]
	v_pk_fma_f32 v[68:69], v[174:175], v[16:17], v[68:69]
	v_pk_fma_f32 v[68:69], v[176:177], v[18:19], v[68:69]
	v_pk_fma_f32 v[68:69], v[178:179], v[20:21], v[68:69]
	v_pk_fma_f32 v[68:69], v[180:181], v[22:23], v[68:69]
	v_pk_fma_f32 v[68:69], v[182:183], v[24:25], v[68:69]
	v_pk_fma_f32 v[68:69], v[184:185], v[26:27], v[68:69]
	v_pk_fma_f32 v[68:69], v[186:187], v[28:29], v[68:69]
	v_pk_fma_f32 v[68:69], v[188:189], v[30:31], v[68:69]
	v_pk_fma_f32 v[68:69], v[190:191], v[32:33], v[68:69]
	v_pk_fma_f32 v[68:69], v[192:193], v[34:35], v[68:69]
	s_waitcnt lgkmcnt(0)
	v_pk_fma_f32 v[68:69], v[194:195], v[36:37], v[68:69]
	v_pk_fma_f32 v[68:69], v[196:197], v[38:39], v[68:69]
	v_pk_fma_f32 v[68:69], v[198:199], v[40:41], v[68:69]
	v_pk_fma_f32 v[68:69], v[200:201], v[42:43], v[68:69]
	v_pk_fma_f32 v[68:69], v[202:203], v[44:45], v[68:69]
	v_pk_fma_f32 v[68:69], v[204:205], v[46:47], v[68:69]
	v_pk_fma_f32 v[68:69], v[206:207], v[48:49], v[68:69]
	v_pk_fma_f32 v[68:69], v[208:209], v[50:51], v[68:69]
	v_pk_fma_f32 v[68:69], v[210:211], v[52:53], v[68:69]
	v_pk_fma_f32 v[68:69], v[212:213], v[54:55], v[68:69]
	v_pk_fma_f32 v[68:69], v[214:215], v[56:57], v[68:69]
	v_pk_fma_f32 v[68:69], v[216:217], v[58:59], v[68:69]
	v_pk_fma_f32 v[68:69], v[218:219], v[60:61], v[68:69]
	v_pk_fma_f32 v[68:69], v[220:221], v[62:63], v[68:69]
	v_pk_fma_f32 v[68:69], v[222:223], v[64:65], v[68:69]
	v_pk_fma_f32 v[68:69], v[224:225], v[66:67], v[68:69]
	v_add_f32_e32 v98, v68, v69
;     ...
;                     s += __shfl_xor(s, 32);
;                 }
;                 g[kb] = s;
;             }
;             selmask = 0u;
; #pragma unroll
;             for (int kb = 0; kb < 15; ++kb) {
;                 int cnt = 0;
; #pragma unroll
;                 for (int k2 = 0; k2 < 15; ++k2) if (k2 != kb) cnt += (g[k2] > g[kb] || (g[k2] == g[kb] && k2 < kb)) ? 1 : 0;
;                 if (kb < j && cnt < 3) selmask |= (1u << kb);
.Lgate_dot_done:
	s_waitcnt lgkmcnt(0)
	v_mov_b32_e32 v4, v84
	v_mov_b32_e32 v5, v85
	v_mov_b32_e32 v6, v86
	v_mov_b32_e32 v7, v87
	v_mov_b32_e32 v8, v88
	v_mov_b32_e32 v9, v89
	v_mov_b32_e32 v10, v90
	v_mov_b32_e32 v11, v91
	v_mov_b32_e32 v12, v92
	v_mov_b32_e32 v13, v93
	v_mov_b32_e32 v14, v94
	v_mov_b32_e32 v15, v95
	v_mov_b32_e32 v16, v96
	v_mov_b32_e32 v17, v97
	v_mov_b32_e32 v18, v98
	s_nop 1
	v_permlane32_swap_b32_e32 v4, v84
	v_permlane32_swap_b32_e32 v5, v85
	v_permlane32_swap_b32_e32 v6, v86
	v_permlane32_swap_b32_e32 v7, v87
	v_permlane32_swap_b32_e32 v8, v88
	v_permlane32_swap_b32_e32 v9, v89
	v_permlane32_swap_b32_e32 v10, v90
	v_permlane32_swap_b32_e32 v11, v91
	v_permlane32_swap_b32_e32 v12, v92
	v_permlane32_swap_b32_e32 v13, v93
	v_permlane32_swap_b32_e32 v14, v94
	v_permlane32_swap_b32_e32 v15, v95
	v_permlane32_swap_b32_e32 v16, v96
	v_permlane32_swap_b32_e32 v17, v97
	v_permlane32_swap_b32_e32 v18, v98
	v_add_f32_e32 v84, v84, v4
	v_add_f32_e32 v85, v85, v5
	v_add_f32_e32 v86, v86, v6
	v_add_f32_e32 v87, v87, v7
	v_add_f32_e32 v88, v88, v8
	v_add_f32_e32 v89, v89, v9
	v_add_f32_e32 v90, v90, v10
	v_add_f32_e32 v91, v91, v11
	v_add_f32_e32 v92, v92, v12
	v_add_f32_e32 v93, v93, v13
	v_add_f32_e32 v94, v94, v14
	v_add_f32_e32 v95, v95, v15
	v_add_f32_e32 v96, v96, v16
	v_add_f32_e32 v97, v97, v17
	v_add_f32_e32 v98, v98, v18
	v_mov_b32_e32 v74, 0
	v_mov_b32_e32 v75, 1
	v_mov_b32_e32 v76, 0xff800000
	v_max3_f32 v72, v84, v85, v86
	v_max3_f32 v72, v72, v87, v88
	v_max3_f32 v72, v72, v89, v90
	v_max3_f32 v72, v72, v91, v92
	v_max3_f32 v72, v72, v93, v94
	v_max3_f32 v72, v72, v95, v96
	v_max3_f32 v72, v72, v97, v98
	v_mov_b32_e32 v73, 15
	v_cmp_eq_f32_e64 s[98:99], v98, v72
	v_cmp_eq_f32_e64 s[100:101], v97, v72
	v_cmp_eq_f32_e64 vcc, v96, v72
	v_cndmask_b32_e64 v73, v73, 14, s[98:99]
	v_cndmask_b32_e64 v73, v73, 13, s[100:101]
	v_cndmask_b32_e64 v73, v73, 12, vcc
	v_cmp_eq_f32_e64 s[98:99], v95, v72
	v_cmp_eq_f32_e64 s[100:101], v94, v72
	v_cmp_eq_f32_e64 vcc, v93, v72
	v_cndmask_b32_e64 v73, v73, 11, s[98:99]
	v_cndmask_b32_e64 v73, v73, 10, s[100:101]
	v_cndmask_b32_e64 v73, v73, 9, vcc
	v_cmp_eq_f32_e64 s[98:99], v92, v72
	v_cmp_eq_f32_e64 s[100:101], v91, v72
	v_cmp_eq_f32_e64 vcc, v90, v72
	v_cndmask_b32_e64 v73, v73, 8, s[98:99]
	v_cndmask_b32_e64 v73, v73, 7, s[100:101]
	v_cndmask_b32_e64 v73, v73, 6, vcc
	v_cmp_eq_f32_e64 s[98:99], v89, v72
	v_cmp_eq_f32_e64 s[100:101], v88, v72
	v_cmp_eq_f32_e64 vcc, v87, v72
	v_cndmask_b32_e64 v73, v73, 5, s[98:99]
	v_cndmask_b32_e64 v73, v73, 4, s[100:101]
	v_cndmask_b32_e64 v73, v73, 3, vcc
	v_cmp_eq_f32_e64 s[98:99], v86, v72
	v_cmp_eq_f32_e64 s[100:101], v85, v72
	v_cmp_eq_f32_e64 vcc, v84, v72
	v_cndmask_b32_e64 v73, v73, 2, s[98:99]
	v_cndmask_b32_e64 v73, v73, 1, s[100:101]
	v_cndmask_b32_e64 v73, v73, 0, vcc
	v_lshlrev_b32_e32 v70, v73, v75
	v_or_b32_e32 v74, v74, v70
	v_cmp_eq_u32_e64 s[98:99], 0, v73
	v_cmp_eq_u32_e64 s[100:101], 1, v73
	v_cmp_eq_u32_e64 vcc, 2, v73
	v_cndmask_b32_e64 v84, v84, v76, s[98:99]
	v_cndmask_b32_e64 v85, v85, v76, s[100:101]
	v_cndmask_b32_e64 v86, v86, v76, vcc
	v_cmp_eq_u32_e64 s[98:99], 3, v73
	v_cmp_eq_u32_e64 s[100:101], 4, v73
	v_cmp_eq_u32_e64 vcc, 5, v73
	v_cndmask_b32_e64 v87, v87, v76, s[98:99]
	v_cndmask_b32_e64 v88, v88, v76, s[100:101]
	v_cndmask_b32_e64 v89, v89, v76, vcc
	v_cmp_eq_u32_e64 s[98:99], 6, v73
	v_cmp_eq_u32_e64 s[100:101], 7, v73
	v_cmp_eq_u32_e64 vcc, 8, v73
	v_cndmask_b32_e64 v90, v90, v76, s[98:99]
	v_cndmask_b32_e64 v91, v91, v76, s[100:101]
	v_cndmask_b32_e64 v92, v92, v76, vcc
	v_cmp_eq_u32_e64 s[98:99], 9, v73
	v_cmp_eq_u32_e64 s[100:101], 10, v73
	v_cmp_eq_u32_e64 vcc, 11, v73
	v_cndmask_b32_e64 v93, v93, v76, s[98:99]
	v_cndmask_b32_e64 v94, v94, v76, s[100:101]
	v_cndmask_b32_e64 v95, v95, v76, vcc
	v_cmp_eq_u32_e64 s[98:99], 12, v73
	v_cmp_eq_u32_e64 s[100:101], 13, v73
	v_cmp_eq_u32_e64 vcc, 14, v73
	v_cndmask_b32_e64 v96, v96, v76, s[98:99]
	v_cndmask_b32_e64 v97, v97, v76, s[100:101]
	v_cndmask_b32_e64 v98, v98, v76, vcc
;     ...
;             selmask = 0u;
; #pragma unroll
;             for (int kb = 0; kb < 15; ++kb) {
;                 int cnt = 0;
; #pragma unroll
;                 for (int k2 = 0; k2 < 15; ++k2) if (k2 != kb) cnt += (g[k2] > g[kb] || (g[k2] == g[kb] && k2 < kb)) ? 1 : 0;
;                 if (kb < j && cnt < 3) selmask |= (1u << kb);
;             }
	v_max3_f32 v72, v84, v85, v86
	v_max3_f32 v72, v72, v87, v88
	v_max3_f32 v72, v72, v89, v90
	v_max3_f32 v72, v72, v91, v92
	v_max3_f32 v72, v72, v93, v94
	v_max3_f32 v72, v72, v95, v96
	v_max3_f32 v72, v72, v97, v98
	v_mov_b32_e32 v73, 15
	v_cmp_eq_f32_e64 s[98:99], v98, v72
	v_cmp_eq_f32_e64 s[100:101], v97, v72
	v_cmp_eq_f32_e64 vcc, v96, v72
	v_cndmask_b32_e64 v73, v73, 14, s[98:99]
	v_cndmask_b32_e64 v73, v73, 13, s[100:101]
	v_cndmask_b32_e64 v73, v73, 12, vcc
	v_cmp_eq_f32_e64 s[98:99], v95, v72
	v_cmp_eq_f32_e64 s[100:101], v94, v72
	v_cmp_eq_f32_e64 vcc, v93, v72
	v_cndmask_b32_e64 v73, v73, 11, s[98:99]
	v_cndmask_b32_e64 v73, v73, 10, s[100:101]
	v_cndmask_b32_e64 v73, v73, 9, vcc
	v_cmp_eq_f32_e64 s[98:99], v92, v72
	v_cmp_eq_f32_e64 s[100:101], v91, v72
	v_cmp_eq_f32_e64 vcc, v90, v72
	v_cndmask_b32_e64 v73, v73, 8, s[98:99]
	v_cndmask_b32_e64 v73, v73, 7, s[100:101]
	v_cndmask_b32_e64 v73, v73, 6, vcc
	v_cmp_eq_f32_e64 s[98:99], v89, v72
	v_cmp_eq_f32_e64 s[100:101], v88, v72
	v_cmp_eq_f32_e64 vcc, v87, v72
	v_cndmask_b32_e64 v73, v73, 5, s[98:99]
	v_cndmask_b32_e64 v73, v73, 4, s[100:101]
	v_cndmask_b32_e64 v73, v73, 3, vcc
	v_cmp_eq_f32_e64 s[98:99], v86, v72
	v_cmp_eq_f32_e64 s[100:101], v85, v72
	v_cmp_eq_f32_e64 vcc, v84, v72
	v_cndmask_b32_e64 v73, v73, 2, s[98:99]
	v_cndmask_b32_e64 v73, v73, 1, s[100:101]
	v_cndmask_b32_e64 v73, v73, 0, vcc
	v_lshlrev_b32_e32 v70, v73, v75
	v_or_b32_e32 v74, v74, v70
	v_cmp_eq_u32_e64 s[98:99], 0, v73
	v_cmp_eq_u32_e64 s[100:101], 1, v73
	v_cmp_eq_u32_e64 vcc, 2, v73
	v_cndmask_b32_e64 v84, v84, v76, s[98:99]
	v_cndmask_b32_e64 v85, v85, v76, s[100:101]
	v_cndmask_b32_e64 v86, v86, v76, vcc
	v_cmp_eq_u32_e64 s[98:99], 3, v73
	v_cmp_eq_u32_e64 s[100:101], 4, v73
	v_cmp_eq_u32_e64 vcc, 5, v73
	v_cndmask_b32_e64 v87, v87, v76, s[98:99]
	v_cndmask_b32_e64 v88, v88, v76, s[100:101]
	v_cndmask_b32_e64 v89, v89, v76, vcc
	v_cmp_eq_u32_e64 s[98:99], 6, v73
	v_cmp_eq_u32_e64 s[100:101], 7, v73
	v_cmp_eq_u32_e64 vcc, 8, v73
	v_cndmask_b32_e64 v90, v90, v76, s[98:99]
	v_cndmask_b32_e64 v91, v91, v76, s[100:101]
	v_cndmask_b32_e64 v92, v92, v76, vcc
	v_cmp_eq_u32_e64 s[98:99], 9, v73
	v_cmp_eq_u32_e64 s[100:101], 10, v73
	v_cmp_eq_u32_e64 vcc, 11, v73
	v_cndmask_b32_e64 v93, v93, v76, s[98:99]
	v_cndmask_b32_e64 v94, v94, v76, s[100:101]
	v_cndmask_b32_e64 v95, v95, v76, vcc
	v_cmp_eq_u32_e64 s[98:99], 12, v73
	v_cmp_eq_u32_e64 s[100:101], 13, v73
	v_cmp_eq_u32_e64 vcc, 14, v73
	v_cndmask_b32_e64 v96, v96, v76, s[98:99]
	v_cndmask_b32_e64 v97, v97, v76, s[100:101]
	v_cndmask_b32_e64 v98, v98, v76, vcc
	v_max3_f32 v72, v84, v85, v86
	v_max3_f32 v72, v72, v87, v88
	v_max3_f32 v72, v72, v89, v90
	v_max3_f32 v72, v72, v91, v92
	v_max3_f32 v72, v72, v93, v94
	v_max3_f32 v72, v72, v95, v96
	v_max3_f32 v72, v72, v97, v98
	v_mov_b32_e32 v73, 15
	v_cmp_eq_f32_e64 s[98:99], v98, v72
	v_cmp_eq_f32_e64 s[100:101], v97, v72
	v_cmp_eq_f32_e64 vcc, v96, v72
	v_cndmask_b32_e64 v73, v73, 14, s[98:99]
	v_cndmask_b32_e64 v73, v73, 13, s[100:101]
	v_cndmask_b32_e64 v73, v73, 12, vcc
	v_cmp_eq_f32_e64 s[98:99], v95, v72
	v_cmp_eq_f32_e64 s[100:101], v94, v72
	v_cmp_eq_f32_e64 vcc, v93, v72
	v_cndmask_b32_e64 v73, v73, 11, s[98:99]
	v_cndmask_b32_e64 v73, v73, 10, s[100:101]
	v_cndmask_b32_e64 v73, v73, 9, vcc
	v_cmp_eq_f32_e64 s[98:99], v92, v72
	v_cmp_eq_f32_e64 s[100:101], v91, v72
	v_cmp_eq_f32_e64 vcc, v90, v72
	v_cndmask_b32_e64 v73, v73, 8, s[98:99]
	v_cndmask_b32_e64 v73, v73, 7, s[100:101]
	v_cndmask_b32_e64 v73, v73, 6, vcc
	v_cmp_eq_f32_e64 s[98:99], v89, v72
	v_cmp_eq_f32_e64 s[100:101], v88, v72
	v_cmp_eq_f32_e64 vcc, v87, v72
	v_cndmask_b32_e64 v73, v73, 5, s[98:99]
	v_cndmask_b32_e64 v73, v73, 4, s[100:101]
	v_cndmask_b32_e64 v73, v73, 3, vcc
	v_cmp_eq_f32_e64 s[98:99], v86, v72
	v_cmp_eq_f32_e64 s[100:101], v85, v72
	v_cmp_eq_f32_e64 vcc, v84, v72
	v_cndmask_b32_e64 v73, v73, 2, s[98:99]
	v_cndmask_b32_e64 v73, v73, 1, s[100:101]
	v_cndmask_b32_e64 v73, v73, 0, vcc
	v_lshlrev_b32_e32 v70, v73, v75
	v_or_b32_e32 v74, v74, v70
	v_mov_b32_e32 v160, v74
